# one static s_setprio 1 for waves 0-3 (older half) for the whole kernel, per-segment toggles deleted, loop alignment preserved; on top of v54
# speedup vs baseline: 1.0097x; 1.0097x over previous
;     __device__ bool tile(int i, Unit& u) const {
;         const long L = (long)i * G + c; if (L >= nwg) return false;
;         int wgid = (int)L; { const int q = nwg / NXCD, r = nwg % NXCD, xcd = wgid % NXCD, off = wgid / NXCD; wgid = (xcd < r ? xcd * (q + 1) : r * (q + 1) + (xcd - r) * q) + off; }
;         const int nig = WGM * nN, gid = wgid / nig, fm = gid * WGM, gsz = (nM - fm) < WGM ? (nM - fm) : WGM;
;         u.pm = fm + ((wgid % nig) % gsz); u.pn = (wgid % nig) / gsz; return true;
; __global__ void __launch_bounds__(512) mk_fwd(Params p0) {
;     ...
;     for (int l = 0; l < 2; ++l) {
;         Params p = p0;
;         { unsigned char* w_ = p0.ws; float* o_ = p0.out; asm volatile("" : "+s"(w_), "+s"(o_)); p.ws = w_; p.out = o_; }
;         float* ssq = (float*)(p.ws + WS_SSQ);
;         bf16_t* XB = (bf16_t*)(p.ws + WS_XB); bf16_t* AD = (bf16_t*)(p.ws + WS_AD); bf16_t* MIX = (bf16_t*)(p.ws + WS_MIX); bf16_t* PROJ = (bf16_t*)(p.ws + WS_PROJ); bf16_t* U = PROJ;
;         const unsigned char* wb = p.ws + WS_W + (size_t)l * W_LAYER;
;         for (int rep = 0; rep < REP_P1; ++rep) {
;             pg8::Gemm g{XB, (const bf16_t*)(wb + WO_IN), DM, DM, DM};
;             small_proj(p, l, G, bx);
;             SchedPlain S; S.o.init(MP / 256, INW / 256, G, bx); S.tA = 256L * DM * 2; S.tB = 256L * DM * 2;
;             EpiProj E{PROJ, ssq + (2 * l) * MPAD, p.gate_bias + l * 2048};
;             pg8::gemm_phase(lds, g, S, E);
.LBB0_140:
	v_writelane_b32 v248, s18, 44
	s_nop 1
	v_writelane_b32 v248, s19, 45
	v_writelane_b32 v248, s30, 46
	s_nop 1
	v_writelane_b32 v248, s31, 47
	v_writelane_b32 v248, s28, 48
	s_nop 1
	v_writelane_b32 v248, s29, 49
	s_or_b64 exec, exec, s[0:1]
	s_not_b32 s0, s81
	s_add_i32 s20, s92, s0
	s_cmpk_lt_i32 s20, 0x68
	s_cselect_b64 s[0:1], -1, 0
	v_writelane_b32 v248, s0, 50
	s_cmpk_lt_i32 s81, 0x680
	s_movk_i32 s15, 0xd1
	v_writelane_b32 v248, s1, 51
	s_cselect_b64 s[0:1], -1, 0
	v_writelane_b32 v248, s0, 52
	s_ashr_i32 s3, s81, 31
	s_ashr_i32 s5, s92, 31
	v_writelane_b32 v248, s1, 53
	s_lshr_b32 s0, s3, 29
	v_writelane_b32 v248, s36, 54
	s_add_i32 s0, s81, s0
	s_ashr_i32 s7, s0, 3
	v_writelane_b32 v247, s46, 0
	v_writelane_b32 v247, s47, 1
	s_and_b32 s0, s0, -8
	v_writelane_b32 v247, s48, 2
	s_sub_i32 s8, s81, s0
	v_writelane_b32 v247, s49, 3
	v_writelane_b32 v247, s50, 4
	s_cmp_lg_u64 s[38:39], 0
	v_writelane_b32 v247, s51, 5
	s_cselect_b64 s[0:1], -1, 0
	v_writelane_b32 v247, s0, 6
	s_and_b32 s9, s92, 7
	v_mov_b64_e32 v[194:195], 0x200
	v_writelane_b32 v247, s1, 7
	s_ashr_i32 s0, s92, 3
	s_mul_i32 s0, s0, s8
	s_add_i32 s10, s0, s7
	s_cmp_lt_i32 s92, 17
	s_cselect_b64 s[0:1], -1, 0
	s_add_i32 s11, s6, 0xffffff80
	s_cmp_lt_i32 s20, 32
	s_cselect_b64 s[12:13], -1, 0
	v_writelane_b32 v247, s12, 8
	s_cmpk_lt_i32 s81, 0x200
	v_writelane_b32 v248, s37, 55
	v_writelane_b32 v247, s13, 9
	s_cselect_b64 s[12:13], -1, 0
	s_lshl_b32 s4, s8, 6
	v_writelane_b32 v247, s12, 10
	s_cmpk_lt_i32 s20, 0x58
	v_writelane_b32 v248, s38, 56
	v_writelane_b32 v247, s13, 11
	s_cselect_b64 s[12:13], -1, 0
	v_writelane_b32 v247, s12, 12
	s_cmpk_lt_i32 s81, 0xb00
	v_writelane_b32 v248, s39, 57
	v_writelane_b32 v247, s13, 13
	s_cselect_b64 s[12:13], -1, 0
	v_writelane_b32 v247, s12, 14
	s_add_u32 s2, s92, s81
	v_writelane_b32 v248, s40, 58
	v_writelane_b32 v247, s13, 15
	v_writelane_b32 v247, s3, 16
	v_writelane_b32 v247, s5, 17
	s_addc_u32 s3, s5, s3
	s_ashr_i32 s5, s2, 31
	s_lshr_b32 s5, s5, 29
	s_add_i32 s5, s2, s5
	s_ashr_i32 s12, s5, 3
	s_and_b32 s5, s5, -8
	s_sub_i32 s13, s2, s5
	s_lshl_b32 s14, s13, 6
	s_cmp_lt_i32 s8, 0
	s_mul_i32 s5, s8, 0x41
	s_cselect_b32 s15, s15, 0xd0
	s_mul_i32 s15, s8, s15
	s_cselect_b32 s16, s5, s4
	s_movk_i32 s4, 0x161
	s_cselect_b32 s17, s4, 0x160
	s_add_i32 s15, s15, s7
	s_mul_hi_i32 s4, s15, 0x4ec4ec4f
	s_lshr_b32 s5, s4, 31
	s_ashr_i32 s4, s4, 5
	s_add_i32 s4, s4, s5
	s_mul_i32 s5, s4, 0x68
	s_sub_i32 s5, s15, s5
	s_lshl_b32 s18, s4, 3
	s_bfe_i32 s4, s5, 0x80000
	s_bfe_u32 s4, s4, 0x3000c
	s_add_i32 s15, s5, s4
	s_bfe_i32 s4, s15, 0x80000
	s_and_b32 s15, s15, 0xf8
	s_sub_i32 s5, s5, s15
	s_sext_i32_i16 s19, s4
	s_sext_i32_i8 s5, s5
	s_add_i32 s22, s18, s5
	s_ashr_i32 s5, s19, 3
	s_lshr_b32 s4, s19, 3
	v_writelane_b32 v247, s5, 18
	s_mov_b32 s18, s22
	s_ashr_i32 s23, s22, 31
	v_writelane_b32 v247, s18, 19
	s_bfe_i64 s[4:5], s[4:5], 0x100000
	s_lshl_b64 s[4:5], s[4:5], 19
	v_writelane_b32 v247, s19, 20
	s_lshl_b64 s[18:19], s[22:23], 19
	v_writelane_b32 v247, s18, 21
	s_cmp_eq_u32 s9, 0
	s_cselect_b32 s10, s10, s81
	v_writelane_b32 v247, s19, 22
	v_writelane_b32 v247, s4, 23
	s_cmpk_lt_i32 s10, 0x110
	v_cmp_lt_i64_e64 s[2:3], s[2:3], v[194:195]
	v_writelane_b32 v247, s5, 24
	s_cselect_b64 s[4:5], -1, 0
	v_writelane_b32 v247, s4, 25
	s_cmp_gt_i32 s10, 15
	v_writelane_b32 v248, s41, 59
	v_writelane_b32 v247, s5, 26
	s_cselect_b64 s[4:5], -1, 0
	s_or_b64 s[0:1], s[0:1], s[4:5]
	v_writelane_b32 v247, s0, 27
	v_writelane_b32 v248, s42, 60
	v_writelane_b32 v248, s43, 61
	v_writelane_b32 v247, s1, 28
	s_lshl_b32 s0, s10, 3
	s_add_i32 s1, s0, 0xffffff80
	s_cmp_gt_i32 s92, 16
	v_writelane_b32 v247, s2, 29
	s_cselect_b32 s0, s1, s0
	s_cselect_b32 s29, s11, s6
	v_writelane_b32 v247, s3, 30
	v_writelane_b32 v247, s0, 31
	s_add_i32 s0, s16, s7
	s_ashr_i32 s1, s0, 31
	s_lshr_b32 s1, s1, 27
	s_add_i32 s1, s0, s1
	s_ashr_i32 s2, s1, 5
	s_andn2_b32 s1, s1, 31
	s_sub_i32 s4, s0, s1
	s_bfe_i32 s0, s4, 0x80000
	s_bfe_u32 s0, s0, 0x3000c
	s_add_i32 s1, s4, s0
	s_bfe_i32 s0, s1, 0x80000
	s_and_b32 s1, s1, 0xf8
	s_sub_i32 s1, s4, s1
	s_lshl_b32 s3, s2, 3
	s_sext_i32_i8 s1, s1
	s_add_i32 s16, s3, s1
	s_mul_i32 s1, s8, s17
	s_sext_i32_i16 s2, s0
	s_add_i32 s1, s1, s7
	s_lshr_b32 s0, s2, 3
	s_ashr_i32 s11, s2, 3
	s_mul_hi_i32 s2, s1, 0x2e8ba2e9
	s_lshr_b32 s5, s2, 31
	s_ashr_i32 s2, s2, 5
	s_add_i32 s2, s2, s5
	s_lshl_b32 s5, s2, 3
	s_mulk_i32 s2, 0xb0
	s_sub_i32 s1, s1, s2
	s_bfe_u32 s2, s1, 0x3001c
	s_add_i32 s6, s1, s2
	s_sext_i32_i16 s7, s6
	s_and_b32 s6, s6, 0xfff8
	s_sub_i32 s1, s1, s6
	s_sext_i32_i16 s1, s1
	s_add_i32 s18, s5, s1
	s_ashr_i32 s1, s7, 3
	v_writelane_b32 v247, s1, 32
	s_sub_i32 s1, 0x80, s3
	s_lshr_b32 s2, s7, 3
	s_min_i32 s5, s1, 8
	s_cmp_lt_i32 s13, 0
	s_mulk_i32 s13, 0x41
	s_cselect_b32 s1, s13, s14
	s_add_i32 s1, s1, s12
	s_ashr_i32 s6, s1, 31
	s_lshr_b32 s6, s6, 27
	s_add_i32 s6, s1, s6
	s_ashr_i32 s17, s16, 31
	s_abs_i32 s9, s92
	s_ashr_i32 s7, s6, 5
	s_andn2_b32 s6, s6, 31
	s_waitcnt lgkmcnt(0)
; __global__ void __launch_bounds__(512) mk_fwd(Params p0) {
;     ...
;             SchedPlain S; S.o.init(MP / 256, INW / 256, G, bx); S.tA = 256L * DM * 2; S.tB = 256L * DM * 2;
;             EpiProj E{PROJ, ssq + (2 * l) * MPAD, p.gate_bias + l * 2048};
;             pg8::gemm_phase(lds, g, S, E);
	v_cvt_f32_u32_e32 v0, s9
	s_lshl_b64 s[12:13], s[16:17], 19
	s_sub_i32 s6, s1, s6
	s_bfe_i64 s[0:1], s[0:1], 0x100000
	v_writelane_b32 v247, s12, 33
	v_rcp_iflag_f32_e32 v0, v0
	s_ashr_i32 s19, s18, 31
	v_writelane_b32 v247, s13, 34
	s_lshl_b64 s[12:13], s[0:1], 18
	v_writelane_b32 v247, s12, 35
	s_lshl_b64 s[0:1], s[0:1], 19
	v_mul_f32_e32 v0, 0x4f7ffffe, v0
	v_writelane_b32 v247, s13, 36
	v_writelane_b32 v247, s0, 37
	v_cvt_u32_f32_e32 v0, v0
	s_lshl_b32 s7, s7, 3
	v_writelane_b32 v247, s1, 38
	s_mov_b32 s0, s18
	v_writelane_b32 v247, s0, 39
	s_sub_i32 s8, 0x80, s7
	s_min_i32 s8, s8, 8
	v_writelane_b32 v247, s1, 40
	s_lshl_b64 s[0:1], s[18:19], 19
	v_writelane_b32 v247, s0, 41
	s_mov_b32 s93, 0
	v_writelane_b32 v248, s44, 62
	v_writelane_b32 v247, s1, 42
	s_bfe_i64 s[0:1], s[2:3], 0x100000
	s_lshl_b64 s[0:1], s[0:1], 19
	v_writelane_b32 v247, s0, 43
	s_mul_hi_i32 s2, s16, 0x160000
	s_movk_i32 s31, 0x80
	v_writelane_b32 v247, s1, 44
	s_sub_i32 s0, 0, s9
	v_readfirstlane_b32 s1, v0
	s_mul_i32 s0, s0, s1
	s_mul_hi_u32 s0, s1, s0
	s_add_i32 s1, s1, s0
	s_mul_hi_u32 s0, s1, 0x680
	s_mul_i32 s0, s0, s9
	s_sub_i32 s0, 0x680, s0
	s_sub_i32 s1, s0, s9
	s_cmp_ge_u32 s0, s9
	s_cselect_b32 s0, s1, s0
	s_sub_i32 s1, s0, s9
	s_cmp_ge_u32 s0, s9
	s_cselect_b32 s0, s1, s0
	s_cmp_ge_i32 s81, s0
	s_cselect_b64 s[12:13], -1, 0
	s_abs_i32 s1, s5
	v_cvt_f32_u32_e32 v0, s1
	v_writelane_b32 v247, s12, 45
	v_mov_b32_e32 v97, 0
	v_mov_b32_e32 v223, 0x358637bd
	v_rcp_iflag_f32_e32 v0, v0
	v_writelane_b32 v247, s13, 46
	v_writelane_b32 v247, s2, 47
	s_sub_i32 s2, s81, s0
	v_mul_f32_e32 v0, 0x4f7ffffe, v0
	v_cvt_u32_f32_e32 v0, v0
	s_lshl_b32 s2, s2, 3
	s_sub_i32 s0, s92, s0
	v_writelane_b32 v247, s2, 48
	s_lshl_b32 s0, s0, 3
	v_writelane_b32 v247, s0, 49
	s_ashr_i32 s0, s4, 31
	s_abs_i32 s2, s4
	s_sub_i32 s4, 0, s1
	v_readfirstlane_b32 s5, v0
	s_mul_i32 s4, s4, s5
	s_mul_hi_u32 s4, s5, s4
	s_add_i32 s5, s5, s4
	s_mul_hi_u32 s4, s2, s5
	s_mul_i32 s4, s4, s1
	s_sub_i32 s2, s2, s4
	s_sub_i32 s4, s2, s1
	s_cmp_ge_u32 s2, s1
	s_cselect_b32 s2, s4, s2
	s_sub_i32 s4, s2, s1
	s_cmp_ge_u32 s2, s1
	s_cselect_b32 s1, s4, s2
	s_abs_i32 s2, s8
	v_cvt_f32_u32_e32 v0, s2
	s_mov_b32 s4, s16
	v_writelane_b32 v247, s4, 50
	s_xor_b32 s1, s1, s0
	v_rcp_iflag_f32_e32 v0, v0
	v_writelane_b32 v247, s5, 51
	s_mul_i32 s4, s16, 0x160000
	v_writelane_b32 v247, s4, 52
	v_mul_f32_e32 v0, 0x4f7ffffe, v0
	v_cvt_u32_f32_e32 v0, v0
	s_mul_hi_i32 s4, s11, 0x160000
	v_writelane_b32 v247, s4, 53
	v_writelane_b32 v247, s11, 54
	s_mul_i32 s4, s11, 0x160000
	s_sub_i32 s0, s1, s0
	v_writelane_b32 v247, s4, 55
	s_add_i32 s0, s3, s0
	s_sub_i32 s3, 0, s2
	v_readfirstlane_b32 s4, v0
	s_mul_i32 s3, s3, s4
	s_mul_hi_u32 s3, s4, s3
	s_abs_i32 s1, s6
	s_add_i32 s4, s4, s3
	s_mul_hi_u32 s3, s1, s4
	s_mul_i32 s3, s3, s2
	s_sub_i32 s1, s1, s3
	v_writelane_b32 v247, s0, 56
	s_ashr_i32 s0, s6, 31
	s_sub_i32 s3, s1, s2
	s_cmp_ge_u32 s1, s2
	s_cselect_b32 s1, s3, s1
	s_sub_i32 s3, s1, s2
	s_cmp_ge_u32 s1, s2
	s_cselect_b32 s1, s3, s1
	s_xor_b32 s1, s1, s0
	s_sub_i32 s0, s1, s0
	s_add_i32 s0, s7, s0
	v_writelane_b32 v247, s0, 57
	s_lshl_b32 s37, s92, 5
	s_lshl_b32 s0, s81, 5
	s_sub_i32 s0, s37, s0
	s_add_i32 s1, s0, -16
	v_writelane_b32 v247, s1, 58
	s_sub_i32 s0, s0, 32
	v_writelane_b32 v247, s0, 59
	s_add_i32 s0, s10, 48
	v_writelane_b32 v247, s0, 60
	v_writelane_b32 v247, s10, 61
	s_add_i32 s0, s10, -16
	v_writelane_b32 v247, s0, 62
	s_lshl_b32 s0, s20, 6
	v_writelane_b32 v247, s0, 63
	s_lshl_b32 s0, s92, 6
	v_writelane_b32 v246, s0, 0
	v_writelane_b32 v246, s20, 1
	s_lshl_b32 s0, s20, 5
	v_writelane_b32 v246, s0, 2
	s_add_i32 s0, 0, 0x23fc0
	v_writelane_b32 v246, s0, 3
	s_add_i32 s0, 0, 0x23fc4
	v_writelane_b32 v246, s0, 4
	v_writelane_b32 v246, s33, 5
	v_writelane_b32 v246, s29, 6
	v_writelane_b32 v246, s37, 7
	v_writelane_b32 v246, s81, 8
	v_mov_b32_e32 v224, 1
	v_mbcnt_hi_u32_b32 v225, -1, v68
	v_mov_b64_e32 v[196:197], 0x680
	v_mov_b64_e32 v[198:199], 0x67f
	v_mov_b32_e32 v226, 0xf149f2ca
	v_mov_b32_e32 v227, 0x1a00
	v_bfrev_b32_e32 v228, 32
	v_mov_b64_e32 v[200:201], 0x1ff
	v_mov_b64_e32 v[202:203], 0xb00
	v_mov_b64_e32 v[204:205], 0xaff
	s_movk_i32 s89, 0x1a00
	s_mov_b32 s35, 0x7838000
	s_mov_b32 s26, 0xb80000
	s_mov_b32 s88, 0xb88000
	s_mov_b32 s97, 0
	s_mov_b64 s[38:39], 0x200
	s_mov_b64 s[94:95], -1
	s_mov_b64 s[4:5], 0x80
	s_mov_b32 s6, 0x3e6d3388
	s_mov_b32 s24, 0x3f07dc22
	s_mov_b32 s28, 0x3f35f0e3
	s_mov_b32 s30, 0xbe11a98e
	s_mov_b32 s34, 0x3e027906
	s_mov_b32 s36, 0xbf38aa3b
	v_writelane_b32 v246, s92, 9
	s_barrier
	v_writelane_b32 v248, s45, 63
	v_writelane_b32 v246, s93, 10
	v_readfirstlane_b32 s32, v222
	s_nop 3
	s_lshr_b32 s32, s32, 6
	s_cmp_lt_u32 s32, 4
	s_cbranch_scc0 .Lmy_prio_done
	s_setprio 1
.Lmy_prio_done:
	s_nop 0
	s_nop 0
	s_nop 0
	s_nop 0
	s_nop 0
	s_nop 0
	s_nop 0
	s_nop 0
	s_nop 0
	s_nop 0
	s_branch .LBB0_144
